# P2 prep_loads: mask-free stepped-address path for the 11 conv-input row loads when chunk >= 2 (on top of v88)
# speedup vs baseline: 1.0002x; 1.0002x over previous
.LBB0_359:
	s_bfe_u32 s33, s33, 0x30003
	v_lshlrev_b32_e32 v0, 3, v155
	s_lshl_b32 s67, s33, 7
	s_andn2_b64 vcc, exec, s[4:5]
	v_and_b32_e32 v2, 0x78, v0
	s_cbranch_vccnz .LBB0_383
	v_lshl_or_b32 v0, s50, 10, v2
	v_or_b32_e32 v0, s67, v0
	v_ashrrev_i32_e32 v1, 31, v0
	v_lshl_add_u64 v[4:5], v[0:1], 4, s[16:17]
	global_load_dwordx4 v[60:63], v[4:5], off offset:48
	global_load_dwordx4 v[56:59], v[4:5], off offset:32
	global_load_dwordx4 v[52:55], v[4:5], off offset:16
	global_load_dwordx4 v[48:51], v[4:5], off
	v_or_b32_e32 v4, 4, v0
	v_ashrrev_i32_e32 v5, 31, v4
	v_lshl_add_u64 v[4:5], v[4:5], 4, s[16:17]
	global_load_dwordx4 v[76:79], v[4:5], off offset:48
	global_load_dwordx4 v[72:75], v[4:5], off offset:32
	global_load_dwordx4 v[68:71], v[4:5], off offset:16
	global_load_dwordx4 v[64:67], v[4:5], off
	s_cmp_ge_i32 s3, 0x50
	s_cbranch_scc1 .Lpl_fast
	v_lshrrev_b32_e32 v3, 1, v155
	v_and_b32_e32 v3, 56, v3
	v_add_u32_e32 v5, -3, v3
	s_lshl_b32 s4, s14, 11
	v_add_u32_e32 v4, s3, v5
	v_mov_b32_e32 v82, v132
	v_mov_b32_e32 v83, v132
	s_add_i32 s66, s4, -16
	v_cmp_lt_i32_e32 vcc, -1, v4
	v_cmp_gt_i32_e64 s[4:5], s65, v5
	v_mov_b32_e32 v80, v132
	v_mov_b32_e32 v81, v132
	v_mov_b64_e32 v[86:87], v[82:83]
	v_lshl_add_u64 v[0:1], v[0:1], 1, s[10:11]
	s_and_b64 s[50:51], s[4:5], vcc
	v_mov_b64_e32 v[84:85], v[80:81]
	s_and_saveexec_b64 s[4:5], s[50:51]
	s_cbranch_execz .LBB0_362
	v_mov_b32_e32 v5, s66
	v_cmp_lt_u32_e32 vcc, 15, v4
	s_nop 1
	v_cndmask_b32_e32 v5, v175, v5, vcc
	v_add_u32_e32 v4, v5, v4
	v_ashrrev_i32_e32 v5, 31, v4
	v_lshlrev_b64 v[4:5], 14, v[4:5]
	v_lshl_add_u64 v[4:5], v[0:1], 0, v[4:5]
	global_load_dwordx4 v[84:87], v[4:5], off

.LBB0_382:
	s_or_b64 exec, exec, s[4:5]
	s_branch .LBB0_383
.Lpl_fast:
	v_lshrrev_b32_e32 v3, 1, v155
	v_and_b32_e32 v3, 56, v3
	s_lshl_b32 s4, s14, 11
	s_add_i32 s66, s4, -16
	s_add_i32 s4, s66, s3
	s_add_i32 s4, s4, -3
	v_add_u32_e32 v4, s4, v3
	v_mov_b32_e32 v5, 0
	v_lshl_add_u64 v[0:1], v[0:1], 1, s[10:11]
	v_lshlrev_b64 v[4:5], 14, v[4:5]
	s_mov_b64 s[50:51], 0x4000
	v_lshl_add_u64 v[4:5], v[0:1], 0, v[4:5]
	global_load_dwordx4 v[84:87], v[4:5], off
	v_lshl_add_u64 v[4:5], v[4:5], 0, s[50:51]
	global_load_dwordx4 v[80:83], v[4:5], off
	v_lshl_add_u64 v[4:5], v[4:5], 0, s[50:51]
	global_load_dwordx4 v[88:91], v[4:5], off
	v_lshl_add_u64 v[4:5], v[4:5], 0, s[50:51]
	global_load_dwordx4 v[92:95], v[4:5], off
	v_lshl_add_u64 v[4:5], v[4:5], 0, s[50:51]
	global_load_dwordx4 v[96:99], v[4:5], off
	v_lshl_add_u64 v[4:5], v[4:5], 0, s[50:51]
	global_load_dwordx4 v[100:103], v[4:5], off
	v_lshl_add_u64 v[4:5], v[4:5], 0, s[50:51]
	global_load_dwordx4 v[104:107], v[4:5], off
	v_lshl_add_u64 v[4:5], v[4:5], 0, s[50:51]
	global_load_dwordx4 v[108:111], v[4:5], off
	v_lshl_add_u64 v[4:5], v[4:5], 0, s[50:51]
	global_load_dwordx4 v[112:115], v[4:5], off
	v_lshl_add_u64 v[4:5], v[4:5], 0, s[50:51]
	global_load_dwordx4 v[116:119], v[4:5], off
	v_lshl_add_u64 v[4:5], v[4:5], 0, s[50:51]
	global_load_dwordx4 v[120:123], v[4:5], off
